# SwiGLU epilogue compute rewritten by hand: 8 independent silu chains per row group (no dependent-chain stalls), saddr stores
# speedup vs baseline: 1.0228x; 1.0028x over previous
.LBB0_257:
	s_or_b64 exec, exec, s[18:19]
	s_waitcnt lgkmcnt(0)
	s_barrier
	ds_read_b32 v182, v170
	ds_read_b32 v183, v170 offset:64
	ds_read_b32 v184, v170 offset:128
	ds_read_b32 v185, v170 offset:192
	ds_read_b32 v186, v170 offset:512
	ds_read_b32 v187, v170 offset:576
	ds_read_b32 v188, v170 offset:640
	ds_read_b32 v189, v170 offset:704
	v_add_u32_e32 v203, s11, v166
	v_lshl_or_b32 v202, s60, 7, v171
	v_lshlrev_b32_e32 v202, 1, v202
	v_mad_u32_u24 v202, v203, s86, v202
	s_waitcnt vmcnt(0) lgkmcnt(0)
	v_fma_f32 v132, v132, v182, v56
	v_fma_f32 v133, v133, v182, v57
	v_fma_f32 v134, v134, v182, v58
	v_fma_f32 v135, v135, v182, v59
	v_fma_f32 v124, v124, v182, v48
	v_fma_f32 v125, v125, v182, v49
	v_fma_f32 v126, v126, v182, v50
	v_fma_f32 v127, v127, v182, v51
	v_fma_f32 v128, v128, v182, v140
	v_fma_f32 v129, v129, v182, v141
	v_fma_f32 v130, v130, v182, v142
	v_fma_f32 v131, v131, v182, v143
	v_fma_f32 v120, v120, v182, v136
	v_fma_f32 v121, v121, v182, v137
	v_fma_f32 v122, v122, v182, v138
	v_fma_f32 v123, v123, v182, v139
	v_mul_f32_e32 v190, 0xbfb8aa3b, v132
	v_mul_f32_e32 v191, 0xbfb8aa3b, v133
	v_mul_f32_e32 v192, 0xbfb8aa3b, v134
	v_mul_f32_e32 v193, 0xbfb8aa3b, v135
	v_mul_f32_e32 v194, 0xbfb8aa3b, v124
	v_mul_f32_e32 v195, 0xbfb8aa3b, v125
	v_mul_f32_e32 v196, 0xbfb8aa3b, v126
	v_mul_f32_e32 v197, 0xbfb8aa3b, v127
	v_exp_f32_e32 v190, v190
	v_exp_f32_e32 v191, v191
	v_exp_f32_e32 v192, v192
	v_exp_f32_e32 v193, v193
	v_exp_f32_e32 v194, v194
	v_exp_f32_e32 v195, v195
	v_exp_f32_e32 v196, v196
	v_exp_f32_e32 v197, v197
	v_add_f32_e32 v190, 1.0, v190
	v_add_f32_e32 v191, 1.0, v191
	v_add_f32_e32 v192, 1.0, v192
	v_add_f32_e32 v193, 1.0, v193
	v_add_f32_e32 v194, 1.0, v194
	v_add_f32_e32 v195, 1.0, v195
	v_add_f32_e32 v196, 1.0, v196
	v_add_f32_e32 v197, 1.0, v197
	v_rcp_f32_e32 v190, v190
	v_rcp_f32_e32 v191, v191
	v_rcp_f32_e32 v192, v192
	v_rcp_f32_e32 v193, v193
	v_rcp_f32_e32 v194, v194
	v_rcp_f32_e32 v195, v195
	v_rcp_f32_e32 v196, v196
	v_rcp_f32_e32 v197, v197
	v_mul_f32_e32 v132, v132, v190
	v_mul_f32_e32 v133, v133, v191
	v_mul_f32_e32 v134, v134, v192
	v_mul_f32_e32 v135, v135, v193
	v_mul_f32_e32 v124, v124, v194
	v_mul_f32_e32 v125, v125, v195
	v_mul_f32_e32 v126, v126, v196
	v_mul_f32_e32 v127, v127, v197
	v_mul_f32_e32 v132, v132, v128
	v_mul_f32_e32 v133, v133, v129
	v_mul_f32_e32 v134, v134, v130
	v_mul_f32_e32 v135, v135, v131
	v_mul_f32_e32 v124, v124, v120
	v_mul_f32_e32 v125, v125, v121
	v_mul_f32_e32 v126, v126, v122
	v_mul_f32_e32 v127, v127, v123
	v_cvt_pk_bf16_f32 v198, v132, v133
	v_cvt_pk_bf16_f32 v199, v134, v135
	v_cvt_pk_bf16_f32 v200, v124, v125
	v_cvt_pk_bf16_f32 v201, v126, v127
	global_store_dwordx4 v202, v[198:201], s[6:7]
	v_fma_f32 v116, v116, v183, v56
	v_fma_f32 v117, v117, v183, v57
	v_fma_f32 v118, v118, v183, v58
	v_fma_f32 v119, v119, v183, v59
	v_fma_f32 v112, v112, v183, v48
	v_fma_f32 v113, v113, v183, v49
	v_fma_f32 v114, v114, v183, v50
	v_fma_f32 v115, v115, v183, v51
	v_fma_f32 v108, v108, v183, v140
	v_fma_f32 v109, v109, v183, v141
	v_fma_f32 v110, v110, v183, v142
	v_fma_f32 v111, v111, v183, v143
	v_fma_f32 v104, v104, v183, v136
	v_fma_f32 v105, v105, v183, v137
	v_fma_f32 v106, v106, v183, v138
	v_fma_f32 v107, v107, v183, v139
	v_mul_f32_e32 v190, 0xbfb8aa3b, v116
	v_mul_f32_e32 v191, 0xbfb8aa3b, v117
	v_mul_f32_e32 v192, 0xbfb8aa3b, v118
	v_mul_f32_e32 v193, 0xbfb8aa3b, v119
	v_mul_f32_e32 v194, 0xbfb8aa3b, v112
	v_mul_f32_e32 v195, 0xbfb8aa3b, v113
	v_mul_f32_e32 v196, 0xbfb8aa3b, v114
	v_mul_f32_e32 v197, 0xbfb8aa3b, v115
	v_exp_f32_e32 v190, v190
	v_exp_f32_e32 v191, v191
	v_exp_f32_e32 v192, v192
	v_exp_f32_e32 v193, v193
	v_exp_f32_e32 v194, v194
	v_exp_f32_e32 v195, v195
	v_exp_f32_e32 v196, v196
	v_exp_f32_e32 v197, v197
	v_add_f32_e32 v190, 1.0, v190
	v_add_f32_e32 v191, 1.0, v191
	v_add_f32_e32 v192, 1.0, v192
	v_add_f32_e32 v193, 1.0, v193
	v_add_f32_e32 v194, 1.0, v194
	v_add_f32_e32 v195, 1.0, v195
	v_add_f32_e32 v196, 1.0, v196
	v_add_f32_e32 v197, 1.0, v197
	v_rcp_f32_e32 v190, v190
	v_rcp_f32_e32 v191, v191
	v_rcp_f32_e32 v192, v192
	v_rcp_f32_e32 v193, v193
	v_rcp_f32_e32 v194, v194
	v_rcp_f32_e32 v195, v195
	v_rcp_f32_e32 v196, v196
	v_rcp_f32_e32 v197, v197
	v_mul_f32_e32 v116, v116, v190
	v_mul_f32_e32 v117, v117, v191
	v_mul_f32_e32 v118, v118, v192
	v_mul_f32_e32 v119, v119, v193
	v_mul_f32_e32 v112, v112, v194
	v_mul_f32_e32 v113, v113, v195
	v_mul_f32_e32 v114, v114, v196
	v_mul_f32_e32 v115, v115, v197
	v_mul_f32_e32 v116, v116, v108
	v_mul_f32_e32 v117, v117, v109
	v_mul_f32_e32 v118, v118, v110
	v_mul_f32_e32 v119, v119, v111
	v_mul_f32_e32 v112, v112, v104
	v_mul_f32_e32 v113, v113, v105
	v_mul_f32_e32 v114, v114, v106
	v_mul_f32_e32 v115, v115, v107
	v_cvt_pk_bf16_f32 v198, v116, v117
	v_cvt_pk_bf16_f32 v199, v118, v119
	v_cvt_pk_bf16_f32 v200, v112, v113
	v_cvt_pk_bf16_f32 v201, v114, v115
	v_add_u32_e32 v203, 0x16000, v202
	s_nop 0
	global_store_dwordx4 v203, v[198:201], s[6:7]
	v_fma_f32 v100, v100, v184, v56
	v_fma_f32 v101, v101, v184, v57
	v_fma_f32 v102, v102, v184, v58
	v_fma_f32 v103, v103, v184, v59
	v_fma_f32 v96, v96, v184, v48
	v_fma_f32 v97, v97, v184, v49
	v_fma_f32 v98, v98, v184, v50
	v_fma_f32 v99, v99, v184, v51
	v_fma_f32 v92, v92, v184, v140
	v_fma_f32 v93, v93, v184, v141
	v_fma_f32 v94, v94, v184, v142
	v_fma_f32 v95, v95, v184, v143
	v_fma_f32 v88, v88, v184, v136
	v_fma_f32 v89, v89, v184, v137
	v_fma_f32 v90, v90, v184, v138
	v_fma_f32 v91, v91, v184, v139
	v_mul_f32_e32 v190, 0xbfb8aa3b, v100
	v_mul_f32_e32 v191, 0xbfb8aa3b, v101
	v_mul_f32_e32 v192, 0xbfb8aa3b, v102
	v_mul_f32_e32 v193, 0xbfb8aa3b, v103
	v_mul_f32_e32 v194, 0xbfb8aa3b, v96
	v_mul_f32_e32 v195, 0xbfb8aa3b, v97
	v_mul_f32_e32 v196, 0xbfb8aa3b, v98
	v_mul_f32_e32 v197, 0xbfb8aa3b, v99
	v_exp_f32_e32 v190, v190
	v_exp_f32_e32 v191, v191
	v_exp_f32_e32 v192, v192
	v_exp_f32_e32 v193, v193
	v_exp_f32_e32 v194, v194
	v_exp_f32_e32 v195, v195
	v_exp_f32_e32 v196, v196
	v_exp_f32_e32 v197, v197
	v_add_f32_e32 v190, 1.0, v190
	v_add_f32_e32 v191, 1.0, v191
	v_add_f32_e32 v192, 1.0, v192
	v_add_f32_e32 v193, 1.0, v193
	v_add_f32_e32 v194, 1.0, v194
	v_add_f32_e32 v195, 1.0, v195
	v_add_f32_e32 v196, 1.0, v196
	v_add_f32_e32 v197, 1.0, v197
	v_rcp_f32_e32 v190, v190
	v_rcp_f32_e32 v191, v191
	v_rcp_f32_e32 v192, v192
	v_rcp_f32_e32 v193, v193
	v_rcp_f32_e32 v194, v194
	v_rcp_f32_e32 v195, v195
	v_rcp_f32_e32 v196, v196
	v_rcp_f32_e32 v197, v197
	v_mul_f32_e32 v100, v100, v190
	v_mul_f32_e32 v101, v101, v191
	v_mul_f32_e32 v102, v102, v192
	v_mul_f32_e32 v103, v103, v193
	v_mul_f32_e32 v96, v96, v194
	v_mul_f32_e32 v97, v97, v195
	v_mul_f32_e32 v98, v98, v196
	v_mul_f32_e32 v99, v99, v197
	v_mul_f32_e32 v100, v100, v92
	v_mul_f32_e32 v101, v101, v93
	v_mul_f32_e32 v102, v102, v94
	v_mul_f32_e32 v103, v103, v95
	v_mul_f32_e32 v96, v96, v88
	v_mul_f32_e32 v97, v97, v89
	v_mul_f32_e32 v98, v98, v90
	v_mul_f32_e32 v99, v99, v91
	v_cvt_pk_bf16_f32 v198, v100, v101
	v_cvt_pk_bf16_f32 v199, v102, v103
	v_cvt_pk_bf16_f32 v200, v96, v97
	v_cvt_pk_bf16_f32 v201, v98, v99
	v_add_u32_e32 v203, 0x2c000, v202
	s_nop 0
	global_store_dwordx4 v203, v[198:201], s[6:7]
	v_fma_f32 v84, v84, v185, v56
	v_fma_f32 v85, v85, v185, v57
	v_fma_f32 v86, v86, v185, v58
	v_fma_f32 v87, v87, v185, v59
	v_fma_f32 v80, v80, v185, v48
	v_fma_f32 v81, v81, v185, v49
	v_fma_f32 v82, v82, v185, v50
	v_fma_f32 v83, v83, v185, v51
	v_fma_f32 v76, v76, v185, v140
	v_fma_f32 v77, v77, v185, v141
	v_fma_f32 v78, v78, v185, v142
	v_fma_f32 v79, v79, v185, v143
	v_fma_f32 v72, v72, v185, v136
	v_fma_f32 v73, v73, v185, v137
	v_fma_f32 v74, v74, v185, v138
	v_fma_f32 v75, v75, v185, v139
	v_mul_f32_e32 v190, 0xbfb8aa3b, v84
	v_mul_f32_e32 v191, 0xbfb8aa3b, v85
	v_mul_f32_e32 v192, 0xbfb8aa3b, v86
	v_mul_f32_e32 v193, 0xbfb8aa3b, v87
	v_mul_f32_e32 v194, 0xbfb8aa3b, v80
	v_mul_f32_e32 v195, 0xbfb8aa3b, v81
	v_mul_f32_e32 v196, 0xbfb8aa3b, v82
	v_mul_f32_e32 v197, 0xbfb8aa3b, v83
	v_exp_f32_e32 v190, v190
	v_exp_f32_e32 v191, v191
	v_exp_f32_e32 v192, v192
	v_exp_f32_e32 v193, v193
	v_exp_f32_e32 v194, v194
	v_exp_f32_e32 v195, v195
	v_exp_f32_e32 v196, v196
	v_exp_f32_e32 v197, v197
	v_add_f32_e32 v190, 1.0, v190
	v_add_f32_e32 v191, 1.0, v191
	v_add_f32_e32 v192, 1.0, v192
	v_add_f32_e32 v193, 1.0, v193
	v_add_f32_e32 v194, 1.0, v194
	v_add_f32_e32 v195, 1.0, v195
	v_add_f32_e32 v196, 1.0, v196
	v_add_f32_e32 v197, 1.0, v197
	v_rcp_f32_e32 v190, v190
	v_rcp_f32_e32 v191, v191
	v_rcp_f32_e32 v192, v192
	v_rcp_f32_e32 v193, v193
	v_rcp_f32_e32 v194, v194
	v_rcp_f32_e32 v195, v195
	v_rcp_f32_e32 v196, v196
	v_rcp_f32_e32 v197, v197
	v_mul_f32_e32 v84, v84, v190
	v_mul_f32_e32 v85, v85, v191
	v_mul_f32_e32 v86, v86, v192
	v_mul_f32_e32 v87, v87, v193
	v_mul_f32_e32 v80, v80, v194
	v_mul_f32_e32 v81, v81, v195
	v_mul_f32_e32 v82, v82, v196
	v_mul_f32_e32 v83, v83, v197
	v_mul_f32_e32 v84, v84, v76
	v_mul_f32_e32 v85, v85, v77
	v_mul_f32_e32 v86, v86, v78
	v_mul_f32_e32 v87, v87, v79
	v_mul_f32_e32 v80, v80, v72
	v_mul_f32_e32 v81, v81, v73
	v_mul_f32_e32 v82, v82, v74
	v_mul_f32_e32 v83, v83, v75
	v_cvt_pk_bf16_f32 v198, v84, v85
	v_cvt_pk_bf16_f32 v199, v86, v87
	v_cvt_pk_bf16_f32 v200, v80, v81
	v_cvt_pk_bf16_f32 v201, v82, v83
	v_add_u32_e32 v203, 0x42000, v202
	s_nop 0
	global_store_dwordx4 v203, v[198:201], s[6:7]
	v_fma_f32 v68, v68, v186, v56
	v_fma_f32 v69, v69, v186, v57
	v_fma_f32 v70, v70, v186, v58
	v_fma_f32 v71, v71, v186, v59
	v_fma_f32 v64, v64, v186, v48
	v_fma_f32 v65, v65, v186, v49
	v_fma_f32 v66, v66, v186, v50
	v_fma_f32 v67, v67, v186, v51
	v_fma_f32 v60, v60, v186, v140
	v_fma_f32 v61, v61, v186, v141
	v_fma_f32 v62, v62, v186, v142
	v_fma_f32 v63, v63, v186, v143
	v_fma_f32 v52, v52, v186, v136
	v_fma_f32 v53, v53, v186, v137
	v_fma_f32 v54, v54, v186, v138
	v_fma_f32 v55, v55, v186, v139
	v_mul_f32_e32 v190, 0xbfb8aa3b, v68
	v_mul_f32_e32 v191, 0xbfb8aa3b, v69
	v_mul_f32_e32 v192, 0xbfb8aa3b, v70
	v_mul_f32_e32 v193, 0xbfb8aa3b, v71
	v_mul_f32_e32 v194, 0xbfb8aa3b, v64
	v_mul_f32_e32 v195, 0xbfb8aa3b, v65
	v_mul_f32_e32 v196, 0xbfb8aa3b, v66
	v_mul_f32_e32 v197, 0xbfb8aa3b, v67
	v_exp_f32_e32 v190, v190
	v_exp_f32_e32 v191, v191
	v_exp_f32_e32 v192, v192
	v_exp_f32_e32 v193, v193
	v_exp_f32_e32 v194, v194
	v_exp_f32_e32 v195, v195
	v_exp_f32_e32 v196, v196
	v_exp_f32_e32 v197, v197
	v_add_f32_e32 v190, 1.0, v190
	v_add_f32_e32 v191, 1.0, v191
	v_add_f32_e32 v192, 1.0, v192
	v_add_f32_e32 v193, 1.0, v193
	v_add_f32_e32 v194, 1.0, v194
	v_add_f32_e32 v195, 1.0, v195
	v_add_f32_e32 v196, 1.0, v196
	v_add_f32_e32 v197, 1.0, v197
	v_rcp_f32_e32 v190, v190
	v_rcp_f32_e32 v191, v191
	v_rcp_f32_e32 v192, v192
	v_rcp_f32_e32 v193, v193
	v_rcp_f32_e32 v194, v194
	v_rcp_f32_e32 v195, v195
	v_rcp_f32_e32 v196, v196
	v_rcp_f32_e32 v197, v197
	v_mul_f32_e32 v68, v68, v190
	v_mul_f32_e32 v69, v69, v191
	v_mul_f32_e32 v70, v70, v192
	v_mul_f32_e32 v71, v71, v193
	v_mul_f32_e32 v64, v64, v194
	v_mul_f32_e32 v65, v65, v195
	v_mul_f32_e32 v66, v66, v196
	v_mul_f32_e32 v67, v67, v197
	v_mul_f32_e32 v68, v68, v60
	v_mul_f32_e32 v69, v69, v61
	v_mul_f32_e32 v70, v70, v62
	v_mul_f32_e32 v71, v71, v63
	v_mul_f32_e32 v64, v64, v52
	v_mul_f32_e32 v65, v65, v53
	v_mul_f32_e32 v66, v66, v54
	v_mul_f32_e32 v67, v67, v55
	v_cvt_pk_bf16_f32 v198, v68, v69
	v_cvt_pk_bf16_f32 v199, v70, v71
	v_cvt_pk_bf16_f32 v200, v64, v65
	v_cvt_pk_bf16_f32 v201, v66, v67
	v_add_u32_e32 v203, 0xb0000, v202
	s_nop 0
	global_store_dwordx4 v203, v[198:201], s[6:7]
	v_fma_f32 v44, v44, v187, v56
	v_fma_f32 v45, v45, v187, v57
	v_fma_f32 v46, v46, v187, v58
	v_fma_f32 v47, v47, v187, v59
	v_fma_f32 v40, v40, v187, v48
	v_fma_f32 v41, v41, v187, v49
	v_fma_f32 v42, v42, v187, v50
	v_fma_f32 v43, v43, v187, v51
	v_fma_f32 v36, v36, v187, v140
	v_fma_f32 v37, v37, v187, v141
	v_fma_f32 v38, v38, v187, v142
	v_fma_f32 v39, v39, v187, v143
	v_fma_f32 v32, v32, v187, v136
	v_fma_f32 v33, v33, v187, v137
	v_fma_f32 v34, v34, v187, v138
	v_fma_f32 v35, v35, v187, v139
	v_mul_f32_e32 v190, 0xbfb8aa3b, v44
	v_mul_f32_e32 v191, 0xbfb8aa3b, v45
	v_mul_f32_e32 v192, 0xbfb8aa3b, v46
	v_mul_f32_e32 v193, 0xbfb8aa3b, v47
	v_mul_f32_e32 v194, 0xbfb8aa3b, v40
	v_mul_f32_e32 v195, 0xbfb8aa3b, v41
	v_mul_f32_e32 v196, 0xbfb8aa3b, v42
	v_mul_f32_e32 v197, 0xbfb8aa3b, v43
	v_exp_f32_e32 v190, v190
	v_exp_f32_e32 v191, v191
	v_exp_f32_e32 v192, v192
	v_exp_f32_e32 v193, v193
	v_exp_f32_e32 v194, v194
	v_exp_f32_e32 v195, v195
	v_exp_f32_e32 v196, v196
	v_exp_f32_e32 v197, v197
	v_add_f32_e32 v190, 1.0, v190
	v_add_f32_e32 v191, 1.0, v191
	v_add_f32_e32 v192, 1.0, v192
	v_add_f32_e32 v193, 1.0, v193
	v_add_f32_e32 v194, 1.0, v194
	v_add_f32_e32 v195, 1.0, v195
	v_add_f32_e32 v196, 1.0, v196
	v_add_f32_e32 v197, 1.0, v197
	v_rcp_f32_e32 v190, v190
	v_rcp_f32_e32 v191, v191
	v_rcp_f32_e32 v192, v192
	v_rcp_f32_e32 v193, v193
	v_rcp_f32_e32 v194, v194
	v_rcp_f32_e32 v195, v195
	v_rcp_f32_e32 v196, v196
	v_rcp_f32_e32 v197, v197
	v_mul_f32_e32 v44, v44, v190
	v_mul_f32_e32 v45, v45, v191
	v_mul_f32_e32 v46, v46, v192
	v_mul_f32_e32 v47, v47, v193
	v_mul_f32_e32 v40, v40, v194
	v_mul_f32_e32 v41, v41, v195
	v_mul_f32_e32 v42, v42, v196
	v_mul_f32_e32 v43, v43, v197
	v_mul_f32_e32 v44, v44, v36
	v_mul_f32_e32 v45, v45, v37
	v_mul_f32_e32 v46, v46, v38
	v_mul_f32_e32 v47, v47, v39
	v_mul_f32_e32 v40, v40, v32
	v_mul_f32_e32 v41, v41, v33
	v_mul_f32_e32 v42, v42, v34
	v_mul_f32_e32 v43, v43, v35
	v_cvt_pk_bf16_f32 v198, v44, v45
	v_cvt_pk_bf16_f32 v199, v46, v47
	v_cvt_pk_bf16_f32 v200, v40, v41
	v_cvt_pk_bf16_f32 v201, v42, v43
	v_add_u32_e32 v203, 0xc6000, v202
	s_nop 0
	global_store_dwordx4 v203, v[198:201], s[6:7]
	v_fma_f32 v28, v28, v188, v56
	v_fma_f32 v29, v29, v188, v57
	v_fma_f32 v30, v30, v188, v58
	v_fma_f32 v31, v31, v188, v59
	v_fma_f32 v24, v24, v188, v48
	v_fma_f32 v25, v25, v188, v49
	v_fma_f32 v26, v26, v188, v50
	v_fma_f32 v27, v27, v188, v51
	v_fma_f32 v20, v20, v188, v140
	v_fma_f32 v21, v21, v188, v141
	v_fma_f32 v22, v22, v188, v142
	v_fma_f32 v23, v23, v188, v143
	v_fma_f32 v16, v16, v188, v136
	v_fma_f32 v17, v17, v188, v137
	v_fma_f32 v18, v18, v188, v138
	v_fma_f32 v19, v19, v188, v139
	v_mul_f32_e32 v190, 0xbfb8aa3b, v28
	v_mul_f32_e32 v191, 0xbfb8aa3b, v29
	v_mul_f32_e32 v192, 0xbfb8aa3b, v30
	v_mul_f32_e32 v193, 0xbfb8aa3b, v31
	v_mul_f32_e32 v194, 0xbfb8aa3b, v24
	v_mul_f32_e32 v195, 0xbfb8aa3b, v25
	v_mul_f32_e32 v196, 0xbfb8aa3b, v26
	v_mul_f32_e32 v197, 0xbfb8aa3b, v27
	v_exp_f32_e32 v190, v190
	v_exp_f32_e32 v191, v191
	v_exp_f32_e32 v192, v192
	v_exp_f32_e32 v193, v193
	v_exp_f32_e32 v194, v194
	v_exp_f32_e32 v195, v195
	v_exp_f32_e32 v196, v196
	v_exp_f32_e32 v197, v197
	v_add_f32_e32 v190, 1.0, v190
	v_add_f32_e32 v191, 1.0, v191
	v_add_f32_e32 v192, 1.0, v192
	v_add_f32_e32 v193, 1.0, v193
	v_add_f32_e32 v194, 1.0, v194
	v_add_f32_e32 v195, 1.0, v195
	v_add_f32_e32 v196, 1.0, v196
	v_add_f32_e32 v197, 1.0, v197
	v_rcp_f32_e32 v190, v190
	v_rcp_f32_e32 v191, v191
	v_rcp_f32_e32 v192, v192
	v_rcp_f32_e32 v193, v193
	v_rcp_f32_e32 v194, v194
	v_rcp_f32_e32 v195, v195
	v_rcp_f32_e32 v196, v196
	v_rcp_f32_e32 v197, v197
	v_mul_f32_e32 v28, v28, v190
	v_mul_f32_e32 v29, v29, v191
	v_mul_f32_e32 v30, v30, v192
	v_mul_f32_e32 v31, v31, v193
	v_mul_f32_e32 v24, v24, v194
	v_mul_f32_e32 v25, v25, v195
	v_mul_f32_e32 v26, v26, v196
	v_mul_f32_e32 v27, v27, v197
	v_mul_f32_e32 v28, v28, v20
	v_mul_f32_e32 v29, v29, v21
	v_mul_f32_e32 v30, v30, v22
	v_mul_f32_e32 v31, v31, v23
	v_mul_f32_e32 v24, v24, v16
	v_mul_f32_e32 v25, v25, v17
	v_mul_f32_e32 v26, v26, v18
	v_mul_f32_e32 v27, v27, v19
	v_cvt_pk_bf16_f32 v198, v28, v29
	v_cvt_pk_bf16_f32 v199, v30, v31
	v_cvt_pk_bf16_f32 v200, v24, v25
	v_cvt_pk_bf16_f32 v201, v26, v27
	v_add_u32_e32 v203, 0xdc000, v202
	s_nop 0
	global_store_dwordx4 v203, v[198:201], s[6:7]
	v_fma_f32 v12, v12, v189, v56
	v_fma_f32 v13, v13, v189, v57
	v_fma_f32 v14, v14, v189, v58
	v_fma_f32 v15, v15, v189, v59
	v_fma_f32 v8, v8, v189, v48
	v_fma_f32 v9, v9, v189, v49
	v_fma_f32 v10, v10, v189, v50
	v_fma_f32 v11, v11, v189, v51
	v_fma_f32 v4, v4, v189, v140
	v_fma_f32 v5, v5, v189, v141
	v_fma_f32 v6, v6, v189, v142
	v_fma_f32 v7, v7, v189, v143
	v_fma_f32 v0, v0, v189, v136
	v_fma_f32 v1, v1, v189, v137
	v_fma_f32 v2, v2, v189, v138
	v_fma_f32 v3, v3, v189, v139
	v_mul_f32_e32 v190, 0xbfb8aa3b, v12
	v_mul_f32_e32 v191, 0xbfb8aa3b, v13
	v_mul_f32_e32 v192, 0xbfb8aa3b, v14
	v_mul_f32_e32 v193, 0xbfb8aa3b, v15
	v_mul_f32_e32 v194, 0xbfb8aa3b, v8
	v_mul_f32_e32 v195, 0xbfb8aa3b, v9
	v_mul_f32_e32 v196, 0xbfb8aa3b, v10
	v_mul_f32_e32 v197, 0xbfb8aa3b, v11
	v_exp_f32_e32 v190, v190
	v_exp_f32_e32 v191, v191
	v_exp_f32_e32 v192, v192
	v_exp_f32_e32 v193, v193
	v_exp_f32_e32 v194, v194
	v_exp_f32_e32 v195, v195
	v_exp_f32_e32 v196, v196
	v_exp_f32_e32 v197, v197
	v_add_f32_e32 v190, 1.0, v190
	v_add_f32_e32 v191, 1.0, v191
	v_add_f32_e32 v192, 1.0, v192
	v_add_f32_e32 v193, 1.0, v193
	v_add_f32_e32 v194, 1.0, v194
	v_add_f32_e32 v195, 1.0, v195
	v_add_f32_e32 v196, 1.0, v196
	v_add_f32_e32 v197, 1.0, v197
	v_rcp_f32_e32 v190, v190
	v_rcp_f32_e32 v191, v191
	v_rcp_f32_e32 v192, v192
	v_rcp_f32_e32 v193, v193
	v_rcp_f32_e32 v194, v194
	v_rcp_f32_e32 v195, v195
	v_rcp_f32_e32 v196, v196
	v_rcp_f32_e32 v197, v197
	v_mul_f32_e32 v12, v12, v190
	v_mul_f32_e32 v13, v13, v191
	v_mul_f32_e32 v14, v14, v192
	v_mul_f32_e32 v15, v15, v193
	v_mul_f32_e32 v8, v8, v194
	v_mul_f32_e32 v9, v9, v195
	v_mul_f32_e32 v10, v10, v196
	v_mul_f32_e32 v11, v11, v197
	v_mul_f32_e32 v12, v12, v4
	v_mul_f32_e32 v13, v13, v5
	v_mul_f32_e32 v14, v14, v6
	v_mul_f32_e32 v15, v15, v7
	v_mul_f32_e32 v8, v8, v0
	v_mul_f32_e32 v9, v9, v1
	v_mul_f32_e32 v10, v10, v2
	v_mul_f32_e32 v11, v11, v3
	v_cvt_pk_bf16_f32 v198, v12, v13
	v_cvt_pk_bf16_f32 v199, v14, v15
	v_cvt_pk_bf16_f32 v200, v8, v9
	v_cvt_pk_bf16_f32 v201, v10, v11
	v_add_u32_e32 v203, 0xf2000, v202
	s_nop 0
	global_store_dwordx4 v203, v[198:201], s[6:7]
	s_andn2_b64 vcc, exec, s[4:5]
	s_cbranch_vccnz .LBB0_248
	s_andn2_b64 vcc, exec, s[0:1]
	s_cbranch_vccnz .LBB0_247
	s_barrier
	s_branch .LBB0_247
